# top-k bisection loops: the staged lgkmcnt waits for the score reads hoisted in front of the loop
# speedup vs baseline: 1.2655x; 1.0001x over previous
.LBB0_890:
	s_or_b64 exec, exec, s[0:1]
	v_readlane_b32 s0, v254, 51
	v_readlane_b32 s4, v254, 29
	s_lshl_b32 s0, s0, 8
	v_readlane_b32 s18, v254, 43
	v_and_b32_e32 v16, 63, v43
	v_readlane_b32 s1, v254, 52
	v_readlane_b32 s19, v254, 44
	s_add_u32 s0, s18, s0
	v_ashrrev_i32_e32 v43, 31, v42
	s_addc_u32 s1, s19, 0
	v_mul_u32_u24_e32 v2, 0x4100, v47
	v_lshlrev_b64 v[0:1], 8, v[42:43]
	v_lshlrev_b32_e32 v3, 2, v16
	v_lshl_add_u64 v[0:1], s[0:1], 0, v[0:1]
	s_cmpk_lt_u32 s71, 0xc00
	s_waitcnt vmcnt(3)
	v_add3_u32 v28, v46, v2, v3
	v_readlane_b32 s5, v254, 30
	v_readlane_b32 s6, v254, 31
	v_readlane_b32 s7, v254, 32
	v_readlane_b32 s8, v254, 33
	v_readlane_b32 s9, v254, 34
	v_readlane_b32 s10, v254, 35
	v_readlane_b32 s11, v254, 36
	v_readlane_b32 s12, v254, 37
	v_readlane_b32 s13, v254, 38
	v_readlane_b32 s14, v254, 39
	v_readlane_b32 s15, v254, 40
	v_readlane_b32 s16, v254, 41
	v_readlane_b32 s17, v254, 42
	s_waitcnt lgkmcnt(0)
	s_barrier
	s_cbranch_scc0 .LBB0_1038
	s_cmpk_lt_u32 s71, 0x800
	s_cbranch_scc0 .LBB0_1043
	s_cmpk_lt_u32 s71, 0x400
	s_cbranch_scc0 .LBB0_1044
	ds_read2st64_b32 v[26:27], v28 offset1:1
	ds_read2st64_b32 v[24:25], v28 offset0:2 offset1:3
	ds_read2st64_b32 v[22:23], v28 offset0:4 offset1:5
	ds_read2st64_b32 v[20:21], v28 offset0:6 offset1:7
	ds_read2st64_b32 v[18:19], v28 offset0:8 offset1:9
	ds_read2st64_b32 v[14:15], v28 offset0:10 offset1:11
	ds_read2st64_b32 v[12:13], v28 offset0:12 offset1:13
	ds_read2st64_b32 v[10:11], v28 offset0:14 offset1:15
	ds_read2st64_b32 v[8:9], v28 offset0:16 offset1:17
	ds_read2st64_b32 v[6:7], v28 offset0:18 offset1:19
	ds_read2st64_b32 v[4:5], v28 offset0:20 offset1:21
	ds_read2st64_b32 v[2:3], v28 offset0:22 offset1:23
	v_or_b32_e32 v29, 0x600, v16
	v_cmp_gt_u32_e32 vcc, s72, v29
	s_waitcnt vmcnt(1)
	v_mov_b32_e32 v36, 0
	v_mov_b32_e32 v37, 0
	s_and_saveexec_b64 s[0:1], vcc
	ds_read_b32 v37, v28 offset:6144
	s_or_b64 exec, exec, s[0:1]
	v_or_b32_e32 v29, 0x640, v16
	v_cmp_gt_u32_e32 vcc, s72, v29
	s_and_saveexec_b64 s[0:1], vcc
	ds_read_b32 v36, v28 offset:6400
	s_or_b64 exec, exec, s[0:1]
	v_or_b32_e32 v29, 0x680, v16
	v_cmp_gt_u32_e32 vcc, s72, v29
	v_mov_b32_e32 v34, 0
	v_mov_b32_e32 v35, 0
	s_and_saveexec_b64 s[0:1], vcc
	ds_read_b32 v35, v28 offset:6656
	s_or_b64 exec, exec, s[0:1]
	v_or_b32_e32 v29, 0x6c0, v16
	v_cmp_gt_u32_e32 vcc, s72, v29
	s_and_saveexec_b64 s[0:1], vcc
	ds_read_b32 v34, v28 offset:6912
	s_or_b64 exec, exec, s[0:1]
	v_or_b32_e32 v29, 0x700, v16
	v_cmp_gt_u32_e32 vcc, s72, v29
	v_mov_b32_e32 v32, 0
	v_mov_b32_e32 v33, 0
	s_and_saveexec_b64 s[0:1], vcc
	ds_read_b32 v33, v28 offset:7168
	s_or_b64 exec, exec, s[0:1]
	v_or_b32_e32 v29, 0x740, v16
	v_cmp_gt_u32_e32 vcc, s72, v29
	s_and_saveexec_b64 s[0:1], vcc
	ds_read_b32 v32, v28 offset:7424
	s_or_b64 exec, exec, s[0:1]
	v_or_b32_e32 v29, 0x780, v16
	v_cmp_gt_u32_e32 vcc, s72, v29
	v_mov_b32_e32 v29, 0
	v_mov_b32_e32 v31, 0
	s_and_saveexec_b64 s[0:1], vcc
	ds_read_b32 v31, v28 offset:7680
	s_or_b64 exec, exec, s[0:1]
	v_or_b32_e32 v30, 0x7c0, v16
	v_cmp_gt_u32_e32 vcc, s72, v30
	s_and_saveexec_b64 s[0:1], vcc
	ds_read_b32 v29, v28 offset:7936
	s_or_b64 exec, exec, s[0:1]
	s_waitcnt vmcnt(0)
	v_mov_b32_e32 v38, 31
	v_mov_b32_e32 v30, 0
	s_waitcnt lgkmcnt(0)
.LBB0_910:
	v_lshlrev_b32_e64 v39, v38, 1
	v_or_b32_e32 v39, v39, v30
	v_cmp_ge_u32_e32 vcc, v26, v39
	s_bcnt1_i32_b64 s0, vcc
	v_cmp_ge_u32_e32 vcc, v27, v39
	s_bcnt1_i32_b64 s1, vcc
	v_cmp_ge_u32_e32 vcc, v24, v39
	s_add_i32 s0, s1, s0
	s_bcnt1_i32_b64 s1, vcc
	v_cmp_ge_u32_e32 vcc, v25, v39
	s_add_i32 s0, s0, s1
	s_bcnt1_i32_b64 s1, vcc
	v_cmp_ge_u32_e32 vcc, v22, v39
	s_add_i32 s0, s0, s1
	s_bcnt1_i32_b64 s1, vcc
	v_cmp_ge_u32_e32 vcc, v23, v39
	s_add_i32 s0, s0, s1
	s_bcnt1_i32_b64 s1, vcc
	v_cmp_ge_u32_e32 vcc, v20, v39
	s_add_i32 s0, s0, s1
	s_bcnt1_i32_b64 s1, vcc
	v_cmp_ge_u32_e32 vcc, v21, v39
	s_add_i32 s0, s0, s1
	s_bcnt1_i32_b64 s1, vcc
	v_cmp_ge_u32_e32 vcc, v18, v39
	s_add_i32 s0, s0, s1
	s_bcnt1_i32_b64 s1, vcc
	v_cmp_ge_u32_e32 vcc, v19, v39
	s_add_i32 s0, s0, s1
	s_bcnt1_i32_b64 s1, vcc
	v_cmp_ge_u32_e32 vcc, v14, v39
	s_add_i32 s0, s0, s1
	s_bcnt1_i32_b64 s1, vcc
	v_cmp_ge_u32_e32 vcc, v15, v39
	s_add_i32 s0, s0, s1
	s_bcnt1_i32_b64 s1, vcc
	v_cmp_ge_u32_e32 vcc, v12, v39
	s_add_i32 s0, s0, s1
	s_bcnt1_i32_b64 s1, vcc
	v_cmp_ge_u32_e32 vcc, v13, v39
	s_add_i32 s0, s0, s1
	s_bcnt1_i32_b64 s1, vcc
	v_cmp_ge_u32_e32 vcc, v10, v39
	s_add_i32 s0, s0, s1
	s_bcnt1_i32_b64 s1, vcc
	v_cmp_ge_u32_e32 vcc, v11, v39
	s_add_i32 s0, s0, s1
	s_bcnt1_i32_b64 s1, vcc
	v_cmp_ge_u32_e32 vcc, v8, v39
	s_add_i32 s0, s0, s1
	s_bcnt1_i32_b64 s1, vcc
	v_cmp_ge_u32_e32 vcc, v9, v39
	s_add_i32 s0, s0, s1
	s_bcnt1_i32_b64 s1, vcc
	v_cmp_ge_u32_e32 vcc, v6, v39
	s_add_i32 s0, s0, s1
	s_bcnt1_i32_b64 s1, vcc
	v_cmp_ge_u32_e32 vcc, v7, v39
	s_add_i32 s0, s0, s1
	s_bcnt1_i32_b64 s1, vcc
	v_cmp_ge_u32_e32 vcc, v4, v39
	s_add_i32 s0, s0, s1
	s_bcnt1_i32_b64 s1, vcc
	v_cmp_ge_u32_e32 vcc, v5, v39
	s_add_i32 s0, s0, s1
	s_bcnt1_i32_b64 s1, vcc
	v_cmp_ge_u32_e32 vcc, v2, v39
	s_add_i32 s0, s0, s1
	s_bcnt1_i32_b64 s1, vcc
	v_cmp_ge_u32_e32 vcc, v3, v39
	s_add_i32 s0, s0, s1
	s_bcnt1_i32_b64 s1, vcc
	v_cmp_ge_u32_e32 vcc, v37, v39
	s_add_i32 s0, s0, s1
	s_bcnt1_i32_b64 s1, vcc
	v_cmp_ge_u32_e32 vcc, v36, v39
	s_add_i32 s0, s0, s1
	s_bcnt1_i32_b64 s1, vcc
	v_cmp_ge_u32_e32 vcc, v35, v39
	s_add_i32 s0, s0, s1
	s_bcnt1_i32_b64 s1, vcc
	v_cmp_ge_u32_e32 vcc, v34, v39
	s_add_i32 s0, s0, s1
	s_bcnt1_i32_b64 s1, vcc
	v_cmp_ge_u32_e32 vcc, v33, v39
	s_add_i32 s0, s0, s1
	s_bcnt1_i32_b64 s1, vcc
	v_cmp_ge_u32_e32 vcc, v32, v39
	s_add_i32 s0, s0, s1
	s_bcnt1_i32_b64 s1, vcc
	v_cmp_ge_u32_e32 vcc, v31, v39
	s_add_i32 s0, s0, s1
	s_bcnt1_i32_b64 s1, vcc
	v_cmp_ge_u32_e32 vcc, v29, v39
	s_add_i32 s0, s0, s1
	s_bcnt1_i32_b64 s1, vcc
	s_add_i32 s2, s0, s1
	s_cmpk_eq_i32 s2, 0x100
	s_cselect_b64 s[0:1], -1, 0
	s_cmpk_lt_u32 s2, 0x100
	s_cselect_b64 vcc, -1, 0
	v_cndmask_b32_e32 v30, v39, v30, vcc
	v_subrev_co_u32_e32 v38, vcc, 1, v38
	s_or_b64 s[0:1], s[0:1], vcc
	s_andn2_b64 vcc, exec, s[0:1]
	s_cbranch_vccnz .LBB0_910
	s_cmpk_eq_i32 s2, 0x100
	s_cbranch_scc1 .Lselfast_32
	v_cmp_gt_u32_e32 vcc, v26, v30
	s_bcnt1_i32_b64 s8, vcc
	v_cmp_gt_u32_e32 vcc, v27, v30
	s_bcnt1_i32_b64 s9, vcc
	v_cmp_gt_u32_e32 vcc, v24, v30
	s_bcnt1_i32_b64 s10, vcc
	v_cmp_gt_u32_e32 vcc, v25, v30
	s_add_i32 s8, s8, s9
	s_bcnt1_i32_b64 s11, vcc
	v_cmp_gt_u32_e32 vcc, v22, v30
	s_add_i32 s8, s8, s10
	s_bcnt1_i32_b64 s64, vcc
	v_cmp_gt_u32_e32 vcc, v23, v30
	s_add_i32 s8, s8, s11
	s_bcnt1_i32_b64 s65, vcc
	v_cmp_gt_u32_e32 vcc, v20, v30
	s_add_i32 s8, s8, s64
	s_bcnt1_i32_b64 s66, vcc
	v_cmp_gt_u32_e32 vcc, v21, v30
	s_add_i32 s8, s8, s65
	s_bcnt1_i32_b64 s67, vcc
	v_cmp_gt_u32_e32 vcc, v18, v30
	s_add_i32 s64, s8, s66
	s_bcnt1_i32_b64 s68, vcc
	v_cmp_gt_u32_e32 vcc, v19, v30
	s_add_i32 s64, s64, s67
	s_bcnt1_i32_b64 s69, vcc
	v_cmp_gt_u32_e32 vcc, v14, v30
	s_add_i32 s64, s64, s68
	s_bcnt1_i32_b64 s73, vcc
	v_cmp_gt_u32_e32 vcc, v15, v30
	s_add_i32 s64, s64, s69
	s_bcnt1_i32_b64 s74, vcc
	v_cmp_gt_u32_e32 vcc, v12, v30
	s_add_i32 s64, s64, s73
	s_bcnt1_i32_b64 s75, vcc
	v_cmp_gt_u32_e32 vcc, v13, v30
	s_add_i32 s64, s64, s74
	s_bcnt1_i32_b64 s76, vcc
	v_cmp_gt_u32_e32 vcc, v10, v30
	s_add_i32 s64, s64, s75
	s_bcnt1_i32_b64 s77, vcc
	v_cmp_gt_u32_e32 vcc, v11, v30
	s_add_i32 s64, s64, s76
	s_bcnt1_i32_b64 s78, vcc
	v_cmp_gt_u32_e32 vcc, v8, v30
	s_add_i32 s64, s64, s77
	s_bcnt1_i32_b64 s79, vcc
	v_cmp_gt_u32_e32 vcc, v9, v30
	s_add_i32 s64, s64, s78
	s_bcnt1_i32_b64 s80, vcc
	v_cmp_gt_u32_e32 vcc, v6, v30
	s_add_i32 s64, s64, s79
	s_bcnt1_i32_b64 s81, vcc
	v_cmp_gt_u32_e32 vcc, v7, v30
	s_add_i32 s64, s64, s80
	s_bcnt1_i32_b64 s82, vcc
	v_cmp_gt_u32_e32 vcc, v4, v30
	s_add_i32 s64, s64, s81
	s_bcnt1_i32_b64 s83, vcc
	v_cmp_gt_u32_e32 vcc, v5, v30
	s_add_i32 s64, s64, s82
	s_bcnt1_i32_b64 s84, vcc
	v_cmp_gt_u32_e32 vcc, v2, v30
	s_add_i32 s64, s64, s83
	s_bcnt1_i32_b64 s85, vcc
	v_cmp_gt_u32_e32 vcc, v3, v30
	s_add_i32 s64, s64, s84
	s_bcnt1_i32_b64 s86, vcc
	v_cmp_gt_u32_e32 vcc, v37, v30
	s_add_i32 s64, s64, s85
	s_bcnt1_i32_b64 s87, vcc
	v_cmp_gt_u32_e32 vcc, v36, v30
	s_add_i32 s64, s64, s86
	s_bcnt1_i32_b64 s88, vcc
	v_cmp_gt_u32_e32 vcc, v35, v30
	s_add_i32 s64, s64, s87
	s_bcnt1_i32_b64 s89, vcc
	v_cmp_gt_u32_e32 vcc, v34, v30
	s_add_i32 s64, s64, s88
	s_bcnt1_i32_b64 s90, vcc
	v_cmp_gt_u32_e32 vcc, v33, v30
	s_add_i32 s64, s64, s89
	s_bcnt1_i32_b64 s91, vcc
	v_cmp_gt_u32_e32 vcc, v32, v30
	s_add_i32 s64, s64, s90
	s_bcnt1_i32_b64 s92, vcc
	v_cmp_gt_u32_e32 vcc, v31, v30
	s_add_i32 s64, s64, s91
	s_bcnt1_i32_b64 s93, vcc
	v_cmp_gt_u32_e32 vcc, v29, v30
	s_add_i32 s64, s64, s92
	s_bcnt1_i32_b64 s94, vcc
	s_add_i32 s64, s64, s93
	s_add_i32 s64, s64, s94
	v_cmp_le_u32_e64 s[62:63], v26, v30
	v_cmp_le_u32_e64 s[60:61], v27, v30
	v_cmp_le_u32_e64 s[58:59], v24, v30
	v_cmp_le_u32_e64 s[56:57], v25, v30
	v_cmp_le_u32_e64 s[54:55], v22, v30
	v_cmp_le_u32_e64 s[52:53], v23, v30
	v_cmp_le_u32_e64 s[50:51], v20, v30
	v_cmp_le_u32_e64 s[48:49], v21, v30
	v_cmp_le_u32_e64 s[46:47], v18, v30
	v_cmp_le_u32_e64 s[44:45], v19, v30
	v_cmp_le_u32_e64 s[42:43], v14, v30
	v_cmp_le_u32_e64 s[40:41], v15, v30
	v_cmp_le_u32_e64 s[38:39], v12, v30
	v_cmp_le_u32_e64 s[36:37], v13, v30
	v_cmp_le_u32_e64 s[34:35], v10, v30
	v_cmp_le_u32_e64 s[30:31], v11, v30
	v_cmp_le_u32_e64 s[28:29], v8, v30
	v_cmp_le_u32_e64 s[26:27], v9, v30
	v_cmp_le_u32_e64 s[24:25], v6, v30
	v_cmp_le_u32_e64 s[22:23], v7, v30
	v_cmp_le_u32_e64 s[4:5], v4, v30
	v_cmp_le_u32_e64 s[0:1], v5, v30
	v_cmp_le_u32_e64 s[2:3], v2, v30
	v_cmp_le_u32_e64 s[6:7], v3, v30
	v_cmp_le_u32_e64 s[20:21], v37, v30
	v_cmp_le_u32_e64 s[18:19], v36, v30
	v_cmp_le_u32_e64 s[16:17], v35, v30
	v_cmp_le_u32_e64 s[14:15], v34, v30
	v_cmp_le_u32_e64 s[12:13], v33, v30
	v_cmp_le_u32_e64 s[10:11], v32, v30
	v_cmp_le_u32_e64 s[8:9], v31, v30
	v_cmp_le_u32_e32 vcc, v29, v30
	s_sub_i32 s73, 0x100, s64
	v_cmp_eq_u32_e64 s[64:65], v26, v30
	s_mov_b64 s[68:69], -1
	s_and_saveexec_b64 s[66:67], s[62:63]
	v_mbcnt_lo_u32_b32 v26, s64, 0
	v_mbcnt_hi_u32_b32 v26, s65, v26
	v_cmp_gt_i32_e64 s[62:63], s73, v26
	s_and_b64 s[62:63], s[64:65], s[62:63]
	s_orn2_b64 s[68:69], s[62:63], exec
	s_or_b64 exec, exec, s[66:67]
	v_cndmask_b32_e64 v26, 0, 1, s[68:69]
	v_cmp_eq_u32_e64 s[66:67], 0, v16
	v_cmp_ne_u32_e64 s[68:69], 0, v26
	s_and_saveexec_b64 s[62:63], s[66:67]
	s_cbranch_execz .LBB0_915
	v_mov_b64_e32 v[38:39], s[68:69]
	global_store_dwordx2 v[0:1], v[38:39], off

.LBB0_1044:
	s_mov_b64 s[66:67], 0
	s_mov_b64 s[2:3], 0xf8
	s_cbranch_execz .LBB0_1158
	ds_read2st64_b32 v[18:19], v28 offset1:1
	ds_read2st64_b32 v[14:15], v28 offset0:2 offset1:3
	ds_read2st64_b32 v[12:13], v28 offset0:4 offset1:5
	ds_read2st64_b32 v[10:11], v28 offset0:6 offset1:7
	ds_read2st64_b32 v[8:9], v28 offset0:8 offset1:9
	ds_read2st64_b32 v[6:7], v28 offset0:10 offset1:11
	ds_read2st64_b32 v[4:5], v28 offset0:12 offset1:13
	ds_read2st64_b32 v[2:3], v28 offset0:14 offset1:15
	v_or_b32_e32 v20, 0x400, v16
	v_cmp_gt_u32_e32 vcc, s72, v20
	v_mov_b32_e32 v27, 0
	v_mov_b32_e32 v29, 0
	s_and_saveexec_b64 s[0:1], vcc
	ds_read_b32 v29, v28 offset:4096
	s_or_b64 exec, exec, s[0:1]
	v_or_b32_e32 v20, 0x440, v16
	v_cmp_gt_u32_e32 vcc, s72, v20
	s_and_saveexec_b64 s[0:1], vcc
	ds_read_b32 v27, v28 offset:4352
	s_or_b64 exec, exec, s[0:1]
	v_or_b32_e32 v20, 0x480, v16
	v_cmp_gt_u32_e32 vcc, s72, v20
	v_mov_b32_e32 v25, 0
	v_mov_b32_e32 v26, 0
	s_and_saveexec_b64 s[0:1], vcc
	ds_read_b32 v26, v28 offset:4608
	s_or_b64 exec, exec, s[0:1]
	v_or_b32_e32 v20, 0x4c0, v16
	v_cmp_gt_u32_e32 vcc, s72, v20
	s_and_saveexec_b64 s[0:1], vcc
	ds_read_b32 v25, v28 offset:4864
	s_or_b64 exec, exec, s[0:1]
	v_or_b32_e32 v20, 0x500, v16
	v_cmp_gt_u32_e32 vcc, s72, v20
	v_mov_b32_e32 v23, 0
	v_mov_b32_e32 v24, 0
	s_and_saveexec_b64 s[0:1], vcc
	ds_read_b32 v24, v28 offset:5120
	s_or_b64 exec, exec, s[0:1]
	v_or_b32_e32 v20, 0x540, v16
	v_cmp_gt_u32_e32 vcc, s72, v20
	s_and_saveexec_b64 s[0:1], vcc
	ds_read_b32 v23, v28 offset:5376
	s_or_b64 exec, exec, s[0:1]
	v_or_b32_e32 v20, 0x580, v16
	v_cmp_gt_u32_e32 vcc, s72, v20
	v_mov_b32_e32 v20, 0
	v_mov_b32_e32 v22, 0
	s_and_saveexec_b64 s[0:1], vcc
	ds_read_b32 v22, v28 offset:5632
	s_or_b64 exec, exec, s[0:1]
	v_or_b32_e32 v21, 0x5c0, v16
	v_cmp_gt_u32_e32 vcc, s72, v21
	s_and_saveexec_b64 s[0:1], vcc
	ds_read_b32 v20, v28 offset:5888
	s_or_b64 exec, exec, s[0:1]
	s_waitcnt vmcnt(2)
	v_mov_b32_e32 v30, 31
	v_mov_b32_e32 v21, 0
	s_waitcnt lgkmcnt(0)
.LBB0_1062:
	v_lshlrev_b32_e64 v31, v30, 1
	v_or_b32_e32 v31, v31, v21
	v_cmp_ge_u32_e32 vcc, v18, v31
	s_bcnt1_i32_b64 s0, vcc
	v_cmp_ge_u32_e32 vcc, v19, v31
	s_bcnt1_i32_b64 s1, vcc
	v_cmp_ge_u32_e32 vcc, v14, v31
	s_add_i32 s0, s1, s0
	s_bcnt1_i32_b64 s1, vcc
	v_cmp_ge_u32_e32 vcc, v15, v31
	s_add_i32 s0, s0, s1
	s_bcnt1_i32_b64 s1, vcc
	v_cmp_ge_u32_e32 vcc, v12, v31
	s_add_i32 s0, s0, s1
	s_bcnt1_i32_b64 s1, vcc
	v_cmp_ge_u32_e32 vcc, v13, v31
	s_add_i32 s0, s0, s1
	s_bcnt1_i32_b64 s1, vcc
	v_cmp_ge_u32_e32 vcc, v10, v31
	s_add_i32 s0, s0, s1
	s_bcnt1_i32_b64 s1, vcc
	v_cmp_ge_u32_e32 vcc, v11, v31
	s_add_i32 s0, s0, s1
	s_bcnt1_i32_b64 s1, vcc
	v_cmp_ge_u32_e32 vcc, v8, v31
	s_add_i32 s0, s0, s1
	s_bcnt1_i32_b64 s1, vcc
	v_cmp_ge_u32_e32 vcc, v9, v31
	s_add_i32 s0, s0, s1
	s_bcnt1_i32_b64 s1, vcc
	v_cmp_ge_u32_e32 vcc, v6, v31
	s_add_i32 s0, s0, s1
	s_bcnt1_i32_b64 s1, vcc
	v_cmp_ge_u32_e32 vcc, v7, v31
	s_add_i32 s0, s0, s1
	s_bcnt1_i32_b64 s1, vcc
	v_cmp_ge_u32_e32 vcc, v4, v31
	s_add_i32 s0, s0, s1
	s_bcnt1_i32_b64 s1, vcc
	v_cmp_ge_u32_e32 vcc, v5, v31
	s_add_i32 s0, s0, s1
	s_bcnt1_i32_b64 s1, vcc
	v_cmp_ge_u32_e32 vcc, v2, v31
	s_add_i32 s0, s0, s1
	s_bcnt1_i32_b64 s1, vcc
	v_cmp_ge_u32_e32 vcc, v3, v31
	s_add_i32 s0, s0, s1
	s_bcnt1_i32_b64 s1, vcc
	v_cmp_ge_u32_e32 vcc, v29, v31
	s_add_i32 s0, s0, s1
	s_bcnt1_i32_b64 s1, vcc
	v_cmp_ge_u32_e32 vcc, v27, v31
	s_add_i32 s0, s0, s1
	s_bcnt1_i32_b64 s1, vcc
	v_cmp_ge_u32_e32 vcc, v26, v31
	s_add_i32 s0, s0, s1
	s_bcnt1_i32_b64 s1, vcc
	v_cmp_ge_u32_e32 vcc, v25, v31
	s_add_i32 s0, s0, s1
	s_bcnt1_i32_b64 s1, vcc
	v_cmp_ge_u32_e32 vcc, v24, v31
	s_add_i32 s0, s0, s1
	s_bcnt1_i32_b64 s1, vcc
	v_cmp_ge_u32_e32 vcc, v23, v31
	s_add_i32 s0, s0, s1
	s_bcnt1_i32_b64 s1, vcc
	v_cmp_ge_u32_e32 vcc, v22, v31
	s_add_i32 s0, s0, s1
	s_bcnt1_i32_b64 s1, vcc
	v_cmp_ge_u32_e32 vcc, v20, v31
	s_add_i32 s0, s0, s1
	s_bcnt1_i32_b64 s1, vcc
	s_add_i32 s2, s0, s1
	s_cmpk_eq_i32 s2, 0x100
	s_cselect_b64 s[0:1], -1, 0
	s_cmpk_lt_u32 s2, 0x100
	s_cselect_b64 vcc, -1, 0
	v_cndmask_b32_e32 v21, v31, v21, vcc
	v_subrev_co_u32_e32 v30, vcc, 1, v30
	s_or_b64 s[0:1], s[0:1], vcc
	s_andn2_b64 vcc, exec, s[0:1]
	s_cbranch_vccnz .LBB0_1062
	s_cmpk_eq_i32 s2, 0x100
	s_cbranch_scc1 .Lselfast_24
	v_cmp_gt_u32_e32 vcc, v18, v21
	s_bcnt1_i32_b64 s50, vcc
	v_cmp_gt_u32_e32 vcc, v19, v21
	s_bcnt1_i32_b64 s51, vcc
	v_cmp_gt_u32_e32 vcc, v14, v21
	v_cmp_gt_u32_e64 s[48:49], v20, v21
	s_bcnt1_i32_b64 s52, vcc
	v_cmp_gt_u32_e32 vcc, v15, v21
	s_bcnt1_i32_b64 s48, s[48:49]
	s_add_i32 s49, s50, s51
	s_bcnt1_i32_b64 s53, vcc
	v_cmp_gt_u32_e32 vcc, v12, v21
	s_add_i32 s49, s49, s52
	s_bcnt1_i32_b64 s54, vcc
	v_cmp_gt_u32_e32 vcc, v13, v21
	s_add_i32 s49, s49, s53
	s_bcnt1_i32_b64 s55, vcc
	v_cmp_gt_u32_e32 vcc, v10, v21
	s_add_i32 s49, s49, s54
	s_bcnt1_i32_b64 s56, vcc
	v_cmp_gt_u32_e32 vcc, v11, v21
	s_add_i32 s49, s49, s55
	s_bcnt1_i32_b64 s57, vcc
	v_cmp_gt_u32_e32 vcc, v8, v21
	s_add_i32 s49, s49, s56
	s_bcnt1_i32_b64 s58, vcc
	v_cmp_gt_u32_e32 vcc, v9, v21
	s_add_i32 s49, s49, s57
	s_bcnt1_i32_b64 s59, vcc
	v_cmp_gt_u32_e32 vcc, v6, v21
	s_add_i32 s49, s49, s58
	s_bcnt1_i32_b64 s60, vcc
	v_cmp_gt_u32_e32 vcc, v7, v21
	s_add_i32 s49, s49, s59
	s_bcnt1_i32_b64 s61, vcc
	v_cmp_gt_u32_e32 vcc, v4, v21
	s_add_i32 s49, s49, s60
	s_bcnt1_i32_b64 s62, vcc
	v_cmp_gt_u32_e32 vcc, v5, v21
	s_add_i32 s49, s49, s61
	s_bcnt1_i32_b64 s63, vcc
	v_cmp_gt_u32_e32 vcc, v2, v21
	s_add_i32 s49, s49, s62
	s_bcnt1_i32_b64 s64, vcc
	v_cmp_gt_u32_e32 vcc, v3, v21
	s_add_i32 s49, s49, s63
	s_bcnt1_i32_b64 s65, vcc
	v_cmp_gt_u32_e32 vcc, v29, v21
	s_add_i32 s49, s49, s64
	s_bcnt1_i32_b64 s66, vcc
	v_cmp_gt_u32_e32 vcc, v27, v21
	s_add_i32 s49, s49, s65
	s_bcnt1_i32_b64 s67, vcc
	v_cmp_gt_u32_e32 vcc, v26, v21
	s_add_i32 s49, s49, s66
	s_bcnt1_i32_b64 s68, vcc
	v_cmp_gt_u32_e32 vcc, v25, v21
	s_add_i32 s49, s49, s67
	s_bcnt1_i32_b64 s69, vcc
	v_cmp_gt_u32_e32 vcc, v24, v21
	s_add_i32 s49, s49, s68
	s_bcnt1_i32_b64 s73, vcc
	v_cmp_gt_u32_e32 vcc, v23, v21
	s_add_i32 s49, s49, s69
	s_bcnt1_i32_b64 s74, vcc
	v_cmp_gt_u32_e32 vcc, v22, v21
	s_add_i32 s49, s49, s73
	s_bcnt1_i32_b64 s75, vcc
	s_add_i32 s49, s49, s74
	s_add_i32 s49, s49, s75
	s_add_i32 s49, s49, s48
	v_cmp_le_u32_e64 s[46:47], v18, v21
	v_cmp_le_u32_e64 s[44:45], v19, v21
	v_cmp_le_u32_e64 s[42:43], v14, v21
	v_cmp_le_u32_e64 s[40:41], v15, v21
	v_cmp_le_u32_e64 s[38:39], v12, v21
	v_cmp_le_u32_e64 s[36:37], v13, v21
	v_cmp_le_u32_e64 s[34:35], v10, v21
	v_cmp_le_u32_e64 s[30:31], v11, v21
	v_cmp_le_u32_e64 s[28:29], v8, v21
	v_cmp_le_u32_e64 s[26:27], v9, v21
	v_cmp_le_u32_e64 s[24:25], v6, v21
	v_cmp_le_u32_e64 s[22:23], v7, v21
	v_cmp_le_u32_e64 s[20:21], v4, v21
	v_cmp_le_u32_e64 s[18:19], v5, v21
	v_cmp_le_u32_e64 s[16:17], v2, v21
	v_cmp_le_u32_e64 s[14:15], v3, v21
	v_cmp_le_u32_e64 s[12:13], v29, v21
	v_cmp_le_u32_e64 s[10:11], v27, v21
	v_cmp_le_u32_e64 s[8:9], v26, v21
	v_cmp_le_u32_e64 s[6:7], v25, v21
	v_cmp_le_u32_e64 s[4:5], v24, v21
	v_cmp_le_u32_e64 s[2:3], v23, v21
	v_cmp_le_u32_e64 s[0:1], v22, v21
	v_cmp_le_u32_e32 vcc, v20, v21
	s_sub_i32 s54, 0x100, s49
	v_cmp_eq_u32_e64 s[48:49], v18, v21
	s_mov_b64 s[52:53], -1
	s_and_saveexec_b64 s[50:51], s[46:47]
	v_mbcnt_lo_u32_b32 v18, s48, 0
	v_mbcnt_hi_u32_b32 v18, s49, v18
	v_cmp_gt_i32_e64 s[46:47], s54, v18
	s_and_b64 s[46:47], s[48:49], s[46:47]
	s_orn2_b64 s[52:53], s[46:47], exec
	s_or_b64 exec, exec, s[50:51]
	v_cndmask_b32_e64 v18, 0, 1, s[52:53]
	v_cmp_eq_u32_e64 s[66:67], 0, v16
	v_cmp_ne_u32_e64 s[50:51], 0, v18
	s_and_saveexec_b64 s[46:47], s[66:67]
	s_cbranch_execz .LBB0_1067
	v_mov_b64_e32 v[30:31], s[50:51]
	global_store_dwordx2 v[0:1], v[30:31], off

.LBB0_1159:
	ds_read2st64_b32 v[8:9], v28 offset1:1
	ds_read2st64_b32 v[6:7], v28 offset0:2 offset1:3
	ds_read2st64_b32 v[4:5], v28 offset0:4 offset1:5
	ds_read2st64_b32 v[2:3], v28 offset0:6 offset1:7
	v_or_b32_e32 v10, 0x200, v16
	v_cmp_gt_u32_e32 vcc, s72, v10
	v_mov_b32_e32 v19, 0
	v_mov_b32_e32 v20, 0
	s_and_saveexec_b64 s[0:1], vcc
	ds_read_b32 v20, v28 offset:2048
	s_or_b64 exec, exec, s[0:1]
	v_or_b32_e32 v10, 0x240, v16
	v_cmp_gt_u32_e32 vcc, s72, v10
	s_and_saveexec_b64 s[0:1], vcc
	ds_read_b32 v19, v28 offset:2304
	s_or_b64 exec, exec, s[0:1]
	v_or_b32_e32 v10, 0x280, v16
	v_cmp_gt_u32_e32 vcc, s72, v10
	v_mov_b32_e32 v15, 0
	v_mov_b32_e32 v18, 0
	s_and_saveexec_b64 s[0:1], vcc
	ds_read_b32 v18, v28 offset:2560
	s_or_b64 exec, exec, s[0:1]
	v_or_b32_e32 v10, 0x2c0, v16
	v_cmp_gt_u32_e32 vcc, s72, v10
	s_and_saveexec_b64 s[0:1], vcc
	ds_read_b32 v15, v28 offset:2816
	s_or_b64 exec, exec, s[0:1]
	v_or_b32_e32 v10, 0x300, v16
	v_cmp_gt_u32_e32 vcc, s72, v10
	v_mov_b32_e32 v13, 0
	v_mov_b32_e32 v14, 0
	s_and_saveexec_b64 s[0:1], vcc
	ds_read_b32 v14, v28 offset:3072
	s_or_b64 exec, exec, s[0:1]
	v_or_b32_e32 v10, 0x340, v16
	v_cmp_gt_u32_e32 vcc, s72, v10
	s_and_saveexec_b64 s[0:1], vcc
	ds_read_b32 v13, v28 offset:3328
	s_or_b64 exec, exec, s[0:1]
	v_or_b32_e32 v10, 0x380, v16
	v_cmp_gt_u32_e32 vcc, s72, v10
	v_mov_b32_e32 v10, 0
	v_mov_b32_e32 v12, 0
	s_and_saveexec_b64 s[0:1], vcc
	ds_read_b32 v12, v28 offset:3584
	s_or_b64 exec, exec, s[0:1]
	v_or_b32_e32 v11, 0x3c0, v16
	v_cmp_gt_u32_e32 vcc, s72, v11
	s_and_saveexec_b64 s[0:1], vcc
	ds_read_b32 v10, v28 offset:3840
	s_or_b64 exec, exec, s[0:1]
	v_mov_b32_e32 v21, 31
	v_mov_b32_e32 v11, 0
	s_waitcnt lgkmcnt(0)
.LBB0_1176:
	v_lshlrev_b32_e64 v22, v21, 1
	v_or_b32_e32 v22, v22, v11
	v_cmp_ge_u32_e32 vcc, v8, v22
	s_bcnt1_i32_b64 s0, vcc
	v_cmp_ge_u32_e32 vcc, v9, v22
	s_bcnt1_i32_b64 s1, vcc
	v_cmp_ge_u32_e32 vcc, v6, v22
	s_add_i32 s0, s1, s0
	s_bcnt1_i32_b64 s1, vcc
	v_cmp_ge_u32_e32 vcc, v7, v22
	s_add_i32 s0, s0, s1
	s_bcnt1_i32_b64 s1, vcc
	v_cmp_ge_u32_e32 vcc, v4, v22
	s_add_i32 s0, s0, s1
	s_bcnt1_i32_b64 s1, vcc
	v_cmp_ge_u32_e32 vcc, v5, v22
	s_add_i32 s0, s0, s1
	s_bcnt1_i32_b64 s1, vcc
	v_cmp_ge_u32_e32 vcc, v2, v22
	s_add_i32 s0, s0, s1
	s_bcnt1_i32_b64 s1, vcc
	v_cmp_ge_u32_e32 vcc, v3, v22
	s_add_i32 s0, s0, s1
	s_bcnt1_i32_b64 s1, vcc
	v_cmp_ge_u32_e32 vcc, v20, v22
	s_add_i32 s0, s0, s1
	s_bcnt1_i32_b64 s1, vcc
	v_cmp_ge_u32_e32 vcc, v19, v22
	s_add_i32 s0, s0, s1
	s_bcnt1_i32_b64 s1, vcc
	v_cmp_ge_u32_e32 vcc, v18, v22
	s_add_i32 s0, s0, s1
	s_bcnt1_i32_b64 s1, vcc
	v_cmp_ge_u32_e32 vcc, v15, v22
	s_add_i32 s0, s0, s1
	s_bcnt1_i32_b64 s1, vcc
	v_cmp_ge_u32_e32 vcc, v14, v22
	s_add_i32 s0, s0, s1
	s_bcnt1_i32_b64 s1, vcc
	v_cmp_ge_u32_e32 vcc, v13, v22
	s_add_i32 s0, s0, s1
	s_bcnt1_i32_b64 s1, vcc
	v_cmp_ge_u32_e32 vcc, v12, v22
	s_add_i32 s0, s0, s1
	s_bcnt1_i32_b64 s1, vcc
	v_cmp_ge_u32_e32 vcc, v10, v22
	s_add_i32 s0, s0, s1
	s_bcnt1_i32_b64 s1, vcc
	s_add_i32 s2, s0, s1
	s_cmpk_eq_i32 s2, 0x100
	s_cselect_b64 s[0:1], -1, 0
	s_cmpk_lt_u32 s2, 0x100
	s_cselect_b64 vcc, -1, 0
	v_cndmask_b32_e32 v11, v22, v11, vcc
	v_subrev_co_u32_e32 v21, vcc, 1, v21
	s_or_b64 s[0:1], s[0:1], vcc
	s_andn2_b64 vcc, exec, s[0:1]
	s_cbranch_vccnz .LBB0_1176
	s_cmpk_eq_i32 s2, 0x100
	s_cbranch_scc1 .Lselfast_16
	v_cmp_gt_u32_e32 vcc, v8, v11
	s_bcnt1_i32_b64 s34, vcc
	v_cmp_gt_u32_e32 vcc, v9, v11
	s_bcnt1_i32_b64 s35, vcc
	v_cmp_gt_u32_e32 vcc, v6, v11
	v_cmp_gt_u32_e64 s[28:29], v10, v11
	s_bcnt1_i32_b64 s36, vcc
	v_cmp_gt_u32_e32 vcc, v7, v11
	s_bcnt1_i32_b64 s28, s[28:29]
	s_add_i32 s29, s34, s35
	s_bcnt1_i32_b64 s37, vcc
	v_cmp_gt_u32_e32 vcc, v4, v11
	s_add_i32 s29, s29, s36
	s_bcnt1_i32_b64 s38, vcc
	v_cmp_gt_u32_e32 vcc, v5, v11
	s_add_i32 s29, s29, s37
	s_bcnt1_i32_b64 s39, vcc
	v_cmp_gt_u32_e32 vcc, v2, v11
	s_add_i32 s29, s29, s38
	s_bcnt1_i32_b64 s40, vcc
	v_cmp_gt_u32_e32 vcc, v3, v11
	s_add_i32 s29, s29, s39
	s_bcnt1_i32_b64 s41, vcc
	v_cmp_gt_u32_e32 vcc, v20, v11
	s_add_i32 s29, s29, s40
	s_bcnt1_i32_b64 s42, vcc
	v_cmp_gt_u32_e32 vcc, v19, v11
	s_add_i32 s29, s29, s41
	s_bcnt1_i32_b64 s43, vcc
	v_cmp_gt_u32_e32 vcc, v18, v11
	s_add_i32 s29, s29, s42
	s_bcnt1_i32_b64 s44, vcc
	v_cmp_gt_u32_e32 vcc, v15, v11
	s_add_i32 s29, s29, s43
	s_bcnt1_i32_b64 s45, vcc
	v_cmp_gt_u32_e32 vcc, v14, v11
	s_add_i32 s29, s29, s44
	s_bcnt1_i32_b64 s46, vcc
	v_cmp_gt_u32_e32 vcc, v13, v11
	s_add_i32 s29, s29, s45
	s_bcnt1_i32_b64 s47, vcc
	v_cmp_gt_u32_e32 vcc, v12, v11
	s_add_i32 s29, s29, s46
	s_bcnt1_i32_b64 s48, vcc
	s_add_i32 s29, s29, s47
	s_add_i32 s29, s29, s48
	s_add_i32 s29, s29, s28
	v_cmp_le_u32_e64 s[30:31], v8, v11
	v_cmp_le_u32_e64 s[26:27], v9, v11
	v_cmp_le_u32_e64 s[24:25], v6, v11
	v_cmp_le_u32_e64 s[22:23], v7, v11
	v_cmp_le_u32_e64 s[20:21], v4, v11
	v_cmp_le_u32_e64 s[18:19], v5, v11
	v_cmp_le_u32_e64 s[16:17], v2, v11
	v_cmp_le_u32_e64 s[14:15], v3, v11
	v_cmp_le_u32_e64 s[12:13], v20, v11
	v_cmp_le_u32_e64 s[10:11], v19, v11
	v_cmp_le_u32_e64 s[8:9], v18, v11
	v_cmp_le_u32_e64 s[6:7], v15, v11
	v_cmp_le_u32_e64 s[4:5], v14, v11
	v_cmp_le_u32_e64 s[2:3], v13, v11
	v_cmp_le_u32_e64 s[0:1], v12, v11
	v_cmp_le_u32_e32 vcc, v10, v11
	s_sub_i32 s38, 0x100, s29
	v_cmp_eq_u32_e64 s[28:29], v8, v11
	s_mov_b64 s[36:37], -1
	s_and_saveexec_b64 s[34:35], s[30:31]
	v_mbcnt_lo_u32_b32 v8, s28, 0
	v_mbcnt_hi_u32_b32 v8, s29, v8
	v_cmp_gt_i32_e64 s[30:31], s38, v8
	s_and_b64 s[30:31], s[28:29], s[30:31]
	s_orn2_b64 s[36:37], s[30:31], exec
	s_or_b64 exec, exec, s[34:35]
	v_cndmask_b32_e64 v8, 0, 1, s[36:37]
	v_cmp_eq_u32_e64 s[66:67], 0, v16
	v_cmp_ne_u32_e64 s[34:35], 0, v8
	s_and_saveexec_b64 s[30:31], s[66:67]
	s_cbranch_execz .LBB0_1181
	v_mov_b64_e32 v[22:23], s[34:35]
	global_store_dwordx2 v[0:1], v[22:23], off

.LBB0_1241:
	ds_read_b32 v10, v28
	v_or_b32_e32 v2, 64, v16
	v_cmp_gt_u32_e32 vcc, s72, v2
	v_mov_b32_e32 v8, 0
	v_mov_b32_e32 v9, 0
	s_and_saveexec_b64 s[0:1], vcc
	ds_read_b32 v9, v28 offset:256
	s_or_b64 exec, exec, s[0:1]
	v_or_b32_e32 v2, 0x80, v16
	v_cmp_gt_u32_e32 vcc, s72, v2
	s_and_saveexec_b64 s[0:1], vcc
	ds_read_b32 v8, v28 offset:512
	s_or_b64 exec, exec, s[0:1]
	v_or_b32_e32 v2, 0xc0, v16
	v_cmp_gt_u32_e32 vcc, s72, v2
	v_mov_b32_e32 v6, 0
	v_mov_b32_e32 v7, 0
	s_and_saveexec_b64 s[0:1], vcc
	ds_read_b32 v7, v28 offset:768
	s_or_b64 exec, exec, s[0:1]
	v_or_b32_e32 v2, 0x100, v16
	v_cmp_gt_u32_e32 vcc, s72, v2
	s_and_saveexec_b64 s[0:1], vcc
	ds_read_b32 v6, v28 offset:1024
	s_or_b64 exec, exec, s[0:1]
	v_or_b32_e32 v2, 0x140, v16
	v_cmp_gt_u32_e32 vcc, s72, v2
	v_mov_b32_e32 v3, 0
	v_mov_b32_e32 v5, 0
	s_and_saveexec_b64 s[0:1], vcc
	ds_read_b32 v5, v28 offset:1280
	s_or_b64 exec, exec, s[0:1]
	v_or_b32_e32 v2, 0x180, v16
	v_cmp_gt_u32_e32 vcc, s72, v2
	s_and_saveexec_b64 s[0:1], vcc
	ds_read_b32 v3, v28 offset:1536
	s_or_b64 exec, exec, s[0:1]
	v_or_b32_e32 v2, 0x1c0, v16
	v_cmp_gt_u32_e32 vcc, s72, v2
	v_mov_b32_e32 v2, 0
	s_and_saveexec_b64 s[0:1], vcc
	ds_read_b32 v2, v28 offset:1792
	s_or_b64 exec, exec, s[0:1]
	s_cmpk_gt_u32 s71, 0xdff
	v_mov_b32_e32 v4, 1
	s_cbranch_scc1 .LBB0_1258
	v_mov_b32_e32 v11, 31
	v_mov_b32_e32 v4, 0
	s_waitcnt lgkmcnt(0)
.LBB0_1257:
	v_lshlrev_b32_e64 v12, v11, 1
	v_or_b32_e32 v12, v12, v4
	v_cmp_ge_u32_e32 vcc, v10, v12
	s_bcnt1_i32_b64 s0, vcc
	v_cmp_ge_u32_e32 vcc, v9, v12
	s_bcnt1_i32_b64 s1, vcc
	v_cmp_ge_u32_e32 vcc, v8, v12
	s_add_i32 s0, s1, s0
	s_bcnt1_i32_b64 s1, vcc
	v_cmp_ge_u32_e32 vcc, v7, v12
	s_add_i32 s0, s0, s1
	s_bcnt1_i32_b64 s1, vcc
	v_cmp_ge_u32_e32 vcc, v6, v12
	s_add_i32 s0, s0, s1
	s_bcnt1_i32_b64 s1, vcc
	v_cmp_ge_u32_e32 vcc, v5, v12
	s_add_i32 s0, s0, s1
	s_bcnt1_i32_b64 s1, vcc
	v_cmp_ge_u32_e32 vcc, v3, v12
	s_add_i32 s0, s0, s1
	s_bcnt1_i32_b64 s1, vcc
	v_cmp_ge_u32_e32 vcc, v2, v12
	s_add_i32 s0, s0, s1
	s_bcnt1_i32_b64 s1, vcc
	s_add_i32 s2, s0, s1
	s_cmpk_eq_i32 s2, 0x100
	s_cselect_b64 s[0:1], -1, 0
	s_cmpk_lt_u32 s2, 0x100
	s_cselect_b64 vcc, -1, 0
	v_cndmask_b32_e32 v4, v12, v4, vcc
	v_subrev_co_u32_e32 v11, vcc, 1, v11
	s_or_b64 s[0:1], s[0:1], vcc
	s_andn2_b64 vcc, exec, s[0:1]
	s_cbranch_vccnz .LBB0_1257
	s_cmpk_eq_i32 s2, 0x100
	s_cbranch_scc1 .Lselfast_8
